# NA second-half bias ladder: the seven waits already implied by the preceding counted wait are deleted in both tile variants
# baseline (speedup 1.0000x reference)
.LBB0_1705:
	s_add_i32 s90, s14, 2
	v_add_u32_e32 v0, s2, v231
	ds_read_b64_tr_b16 v[194:195], v0 offset:24576
	ds_read_b64_tr_b16 v[196:197], v0 offset:25088
	s_waitcnt lgkmcnt(9)
	v_mfma_f32_32x32x16_bf16 v[96:111], v[190:193], v[142:145], 0
	v_add_f32_e32 v2, v64, v65
	v_add_f32_e32 v2, v66, v2
	v_add_f32_e32 v2, v67, v2
	v_add_f32_e32 v2, v68, v2
	v_add_f32_e32 v2, v69, v2
	v_cvt_pk_bf16_f32 v158, v64, v65
	v_cvt_pk_bf16_f32 v159, v66, v67
	ds_read_b64_tr_b16 v[10:11], v0 offset:28672
	ds_read_b64_tr_b16 v[12:13], v0 offset:29184
	s_waitcnt lgkmcnt(10)
	v_mfma_f32_32x32x16_bf16 v[114:129], v[182:185], v[142:145], 0
	v_add_f32_e32 v2, v70, v2
	v_add_f32_e32 v2, v71, v2
	v_add_f32_e32 v2, v72, v2
	v_add_f32_e32 v6, v73, v2
	v_cvt_pk_bf16_f32 v160, v68, v69
	v_cvt_pk_bf16_f32 v161, v70, v71
	ds_read_b64_tr_b16 v[2:3], v0 offset:25600
	ds_read_b64_tr_b16 v[4:5], v0 offset:26112
	s_waitcnt lgkmcnt(11)
	v_mfma_f32_32x32x16_bf16 v[96:111], v[186:189], v[138:141], v[96:111]
	v_add_f32_e32 v6, v74, v6
	v_add_f32_e32 v6, v75, v6
	v_add_f32_e32 v6, v76, v6
	v_add_f32_e32 v14, v77, v6
	v_cvt_pk_bf16_f32 v154, v72, v73
	v_cvt_pk_bf16_f32 v155, v74, v75
	ds_read_b64_tr_b16 v[6:7], v0 offset:29696
	ds_read_b64_tr_b16 v[8:9], v0 offset:30208
	s_waitcnt lgkmcnt(12)
	v_mfma_f32_32x32x16_bf16 v[114:129], v[178:181], v[138:141], v[114:129]
	v_add_f32_e32 v14, v78, v14
	v_add_f32_e32 v14, v79, v14
	v_add_f32_e32 v14, v80, v14
	v_add_f32_e32 v14, v81, v14
	v_cvt_pk_bf16_f32 v156, v76, v77
	v_cvt_pk_bf16_f32 v157, v78, v79
	ds_read_b64_tr_b16 v[178:179], v0 offset:26624
	ds_read_b64_tr_b16 v[180:181], v0 offset:27136
	s_waitcnt lgkmcnt(13)
	v_mfma_f32_32x32x16_bf16 v[96:111], v[174:177], v[134:137], v[96:111]
	v_add_f32_e32 v14, v82, v14
	v_add_f32_e32 v14, v83, v14
	v_add_f32_e32 v14, v84, v14
	v_add_f32_e32 v14, v85, v14
	v_cvt_pk_bf16_f32 v150, v80, v81
	v_cvt_pk_bf16_f32 v151, v82, v83
	ds_read_b64_tr_b16 v[174:175], v0 offset:30720
	ds_read_b64_tr_b16 v[176:177], v0 offset:31232
	s_waitcnt lgkmcnt(14)
	v_mfma_f32_32x32x16_bf16 v[114:129], v[170:173], v[134:137], v[114:129]
	v_add_f32_e32 v14, v86, v14
	v_add_f32_e32 v14, v87, v14
	v_add_f32_e32 v14, v88, v14
	v_add_f32_e32 v14, v89, v14
	v_cvt_pk_bf16_f32 v152, v84, v85
	v_cvt_pk_bf16_f32 v153, v86, v87
	ds_read_b64_tr_b16 v[170:171], v0 offset:27648
	ds_read_b64_tr_b16 v[172:173], v0 offset:28160
	s_waitcnt lgkmcnt(14)
	v_mfma_f32_32x32x16_bf16 v[96:111], v[166:169], v[130:133], v[96:111]
	v_add_f32_e32 v14, v90, v14
	v_add_f32_e32 v14, v91, v14
	v_add_f32_e32 v14, v92, v14
	v_add_f32_e32 v14, v93, v14
	v_cvt_pk_bf16_f32 v146, v88, v89
	v_cvt_pk_bf16_f32 v147, v90, v91
	ds_read_b64_tr_b16 v[166:167], v0 offset:31744
	ds_read_b64_tr_b16 v[168:169], v0 offset:32256
	v_mfma_f32_32x32x16_bf16 v[114:129], v[162:165], v[130:133], v[114:129]
	v_add_f32_e32 v0, v94, v14
	v_add_f32_e32 v0, v95, v0
	v_add_f32_e32 v0, 0, v0
	v_cvt_pk_bf16_f32 v148, v92, v93
	v_cvt_pk_bf16_f32 v149, v94, v95
	s_add_i32 s7, s14, 5
	s_cmp_lt_i32 s7, s0
	s_cselect_b32 s2, s7, s12
	s_cmp_gt_i32 s7, s6
	s_cselect_b32 s9, s95, 0
	s_cselect_b32 s8, s13, 0
	s_lshl_b64 s[10:11], s[2:3], 18
	v_lshl_add_u64 v[14:15], v[214:215], 0, s[10:11]
	s_add_i32 s2, s15, s97
	v_lshl_add_u64 v[14:15], s[8:9], 1, v[14:15]
	s_mov_b32 s7, m0
	s_mov_b32 m0, s2
	s_nop 0
	global_load_lds_dwordx4 v[14:15], off
	s_mov_b32 m0, s7
	s_add_i32 s2, s14, 3
	s_cmp_ge_i32 s2, s0
	s_cselect_b64 s[34:35], -1, 0
	s_cmp_lt_i32 s2, s0
	s_cselect_b32 s2, s2, s12
	s_cmp_ge_i32 s90, s6
	s_cselect_b64 s[36:37], -1, 0
	s_cmp_lt_i32 s90, s6
	s_cselect_b32 s9, 0, s95
	s_cselect_b32 s8, 0, s13
	s_lshl_b64 s[10:11], s[2:3], 18
	v_lshl_add_u64 v[14:15], v[216:217], 0, s[10:11]
	s_add_i32 s2, s89, s92
	v_lshl_add_u64 v[14:15], s[8:9], 1, v[14:15]
	s_mov_b32 s7, m0
	s_mov_b32 m0, s2
	s_nop 0
	global_load_lds_dwordx4 v[14:15], off
	s_mov_b32 m0, s7
	s_cmp_gt_i32 s90, s6
	s_cselect_b64 s[8:9], -1, 0
	v_pk_add_f32 v[112:113], v[96:97], v[218:219] op_sel_hi:[1,0] neg_lo:[0,1] neg_hi:[0,1]
	v_pk_add_f32 v[96:97], v[114:115], v[218:219] op_sel_hi:[1,0] neg_lo:[0,1] neg_hi:[0,1]
	v_pk_add_f32 v[114:115], v[98:99], v[218:219] op_sel_hi:[1,0] neg_lo:[0,1] neg_hi:[0,1]
	v_pk_add_f32 v[98:99], v[116:117], v[218:219] op_sel_hi:[1,0] neg_lo:[0,1] neg_hi:[0,1]
	v_pk_add_f32 v[116:117], v[100:101], v[218:219] op_sel_hi:[1,0] neg_lo:[0,1] neg_hi:[0,1]
	v_pk_add_f32 v[100:101], v[118:119], v[218:219] op_sel_hi:[1,0] neg_lo:[0,1] neg_hi:[0,1]
	v_pk_add_f32 v[118:119], v[102:103], v[218:219] op_sel_hi:[1,0] neg_lo:[0,1] neg_hi:[0,1]
	v_pk_add_f32 v[102:103], v[120:121], v[218:219] op_sel_hi:[1,0] neg_lo:[0,1] neg_hi:[0,1]
	v_pk_add_f32 v[120:121], v[104:105], v[218:219] op_sel_hi:[1,0] neg_lo:[0,1] neg_hi:[0,1]
	v_pk_add_f32 v[104:105], v[122:123], v[218:219] op_sel_hi:[1,0] neg_lo:[0,1] neg_hi:[0,1]
	v_pk_add_f32 v[122:123], v[106:107], v[218:219] op_sel_hi:[1,0] neg_lo:[0,1] neg_hi:[0,1]
	v_pk_add_f32 v[106:107], v[124:125], v[218:219] op_sel_hi:[1,0] neg_lo:[0,1] neg_hi:[0,1]
	v_pk_add_f32 v[124:125], v[108:109], v[218:219] op_sel_hi:[1,0] neg_lo:[0,1] neg_hi:[0,1]
	v_pk_add_f32 v[108:109], v[126:127], v[218:219] op_sel_hi:[1,0] neg_lo:[0,1] neg_hi:[0,1]
	v_pk_add_f32 v[126:127], v[110:111], v[218:219] op_sel_hi:[1,0] neg_lo:[0,1] neg_hi:[0,1]
	v_pk_add_f32 v[110:111], v[128:129], v[218:219] op_sel_hi:[1,0] neg_lo:[0,1] neg_hi:[0,1]
	s_mov_b64 s[10:11], -1
	s_and_b64 vcc, exec, s[8:9]
	s_cbranch_vccnz .LBB0_1742
	s_add_i32 s2, s96, s14
	s_add_i32 s2, s2, 2
	s_cmp_lt_u32 s2, s93
	s_cselect_b64 s[10:11], -1, 0
	s_cmp_gt_u32 s2, s1
	s_cselect_b64 vcc, -1, 0
	s_or_b64 s[10:11], s[10:11], vcc
	s_and_b64 vcc, exec, s[10:11]
	s_cbranch_vccnz .LBB0_1740
	ds_read_b32 v14, v207 offset:128
	ds_read_b32 v235, v207
	ds_read_b32 v15, v207 offset:132
	ds_read_b32 v236, v207 offset:4
	ds_read_b32 v17, v207 offset:136
	ds_read_b32 v237, v207 offset:8
	ds_read_b32 v18, v207 offset:140
	ds_read_b32 v238, v207 offset:12
	ds_read_b32 v19, v207 offset:160
	ds_read_b32 v239, v207 offset:32
	ds_read_b32 v20, v207 offset:164
	ds_read_b32 v240, v207 offset:36
	ds_read_b32 v21, v207 offset:168
	ds_read_b32 v241, v207 offset:40
	ds_read_b32 v22, v207 offset:172
	ds_read_b32 v242, v207 offset:44
	s_waitcnt lgkmcnt(8)
	v_add_f32_e32 v251, v112, v235
	v_cndmask_b32_e64 v64, v16, v251, s[40:41]
	v_add_f32_e32 v251, v113, v236
	v_cndmask_b32_e64 v65, v16, v251, s[44:45]
	v_add_f32_e32 v251, v114, v237
	v_cndmask_b32_e64 v66, v16, v251, s[48:49]
	v_add_f32_e32 v251, v115, v238
	v_cndmask_b32_e64 v67, v16, v251, s[52:53]
	ds_read_b32 v23, v207 offset:192
	ds_read_b32 v243, v207 offset:64
	ds_read_b32 v24, v207 offset:196
	ds_read_b32 v244, v207 offset:68
	ds_read_b32 v25, v207 offset:200
	ds_read_b32 v245, v207 offset:72
	ds_read_b32 v26, v207 offset:204
	ds_read_b32 v246, v207 offset:76
	s_waitcnt lgkmcnt(8)
	v_add_f32_e32 v251, v116, v239
	v_cndmask_b32_e64 v68, v16, v251, s[56:57]
	v_add_f32_e32 v251, v117, v240
	v_cndmask_b32_e64 v69, v16, v251, s[60:61]
	v_add_f32_e32 v251, v118, v241
	v_cndmask_b32_e64 v70, v16, v251, s[64:65]
	v_add_f32_e32 v251, v119, v242
	v_cndmask_b32_e64 v71, v16, v251, s[68:69]
	ds_read_b32 v27, v207 offset:224
	ds_read_b32 v247, v207 offset:96
	ds_read_b32 v28, v207 offset:228
	ds_read_b32 v248, v207 offset:100
	ds_read_b32 v29, v207 offset:232
	ds_read_b32 v249, v207 offset:104
	ds_read_b32 v30, v207 offset:236
	ds_read_b32 v250, v207 offset:108
	s_waitcnt lgkmcnt(8)
	v_add_f32_e32 v251, v120, v243
	v_cndmask_b32_e64 v72, v16, v251, s[16:17]
	v_add_f32_e32 v251, v121, v244
	v_cndmask_b32_e64 v73, v16, v251, s[18:19]
	v_add_f32_e32 v251, v122, v245
	v_cndmask_b32_e64 v74, v16, v251, s[20:21]
	v_add_f32_e32 v251, v123, v246
	v_cndmask_b32_e64 v75, v16, v251, s[22:23]
	v_add_f32_e32 v14, v96, v14
	v_cndmask_b32_e64 v80, v16, v14, s[42:43]
	v_add_f32_e32 v14, v97, v15
	v_cndmask_b32_e64 v81, v16, v14, s[46:47]
	v_add_f32_e32 v14, v98, v17
	v_cndmask_b32_e64 v82, v16, v14, s[50:51]
	v_add_f32_e32 v14, v99, v18
	v_cndmask_b32_e64 v83, v16, v14, s[54:55]
	v_add_f32_e32 v14, v100, v19
	v_cndmask_b32_e64 v84, v16, v14, s[58:59]
	v_add_f32_e32 v14, v101, v20
	v_cndmask_b32_e64 v85, v16, v14, s[62:63]
	v_add_f32_e32 v14, v102, v21
	v_cndmask_b32_e64 v86, v16, v14, s[66:67]
	v_add_f32_e32 v14, v103, v22
	v_cndmask_b32_e64 v87, v16, v14, s[70:71]
	s_waitcnt lgkmcnt(7)
	v_add_f32_e32 v14, v104, v23
	v_cndmask_b32_e64 v88, v16, v14, s[72:73]
	s_waitcnt lgkmcnt(6)
	v_add_f32_e32 v14, v105, v24
	v_cndmask_b32_e64 v89, v16, v14, s[74:75]
	s_waitcnt lgkmcnt(5)
	v_add_f32_e32 v14, v106, v25
	v_cndmask_b32_e64 v90, v16, v14, s[76:77]
	s_waitcnt lgkmcnt(4)
	v_add_f32_e32 v14, v107, v26
	v_cndmask_b32_e64 v91, v16, v14, s[78:79]
	s_waitcnt lgkmcnt(3)
	v_add_f32_e32 v14, v108, v27
	v_cndmask_b32_e64 v92, v16, v14, s[80:81]
	s_waitcnt lgkmcnt(2)
	v_add_f32_e32 v14, v109, v28
	v_cndmask_b32_e64 v93, v16, v14, s[82:83]
	s_waitcnt lgkmcnt(1)
	v_add_f32_e32 v14, v110, v29
	v_cndmask_b32_e64 v94, v16, v14, s[84:85]
	s_waitcnt lgkmcnt(0)
	v_add_f32_e32 v14, v111, v30
	v_cndmask_b32_e64 v95, v16, v14, s[86:87]
	v_add_f32_e32 v251, v124, v247
	v_cndmask_b32_e64 v76, v16, v251, s[24:25]
	v_add_f32_e32 v251, v125, v248
	v_cndmask_b32_e64 v77, v16, v251, s[26:27]
	v_add_f32_e32 v251, v126, v249
	v_cndmask_b32_e64 v78, v16, v251, s[28:29]
	v_add_f32_e32 v251, v127, v250
	v_cndmask_b32_e64 v79, v16, v251, s[30:31]
	s_branch .LBB0_1741

.LBB0_1753:
	s_add_i32 s2, s96, s14
	s_add_i32 s2, s2, 3
	s_cmp_lt_u32 s2, s93
	s_cselect_b64 s[8:9], -1, 0
	s_cmp_gt_u32 s2, s1
	s_cselect_b64 s[10:11], -1, 0
	s_or_b64 s[8:9], s[8:9], s[10:11]
	s_and_b64 vcc, exec, s[8:9]
	s_cbranch_vccnz .LBB0_1788
	ds_read_b32 v17, v207 offset:252
	ds_read_b32 v235, v207 offset:124
	ds_read_b32 v18, v207 offset:256
	ds_read_b32 v236, v207 offset:128
	ds_read_b32 v19, v207 offset:260
	ds_read_b32 v237, v207 offset:132
	ds_read_b32 v20, v207 offset:264
	ds_read_b32 v238, v207 offset:136
	ds_read_b32 v21, v207 offset:284
	ds_read_b32 v239, v207 offset:156
	ds_read_b32 v22, v207 offset:288
	ds_read_b32 v240, v207 offset:160
	ds_read_b32 v23, v207 offset:292
	ds_read_b32 v241, v207 offset:164
	ds_read_b32 v24, v207 offset:296
	ds_read_b32 v242, v207 offset:168
	s_waitcnt lgkmcnt(8)
	v_add_f32_e32 v251, v112, v235
	v_cndmask_b32_e64 v64, v16, v251, s[40:41]
	v_add_f32_e32 v251, v113, v236
	v_cndmask_b32_e64 v65, v16, v251, s[44:45]
	v_add_f32_e32 v251, v114, v237
	v_cndmask_b32_e64 v66, v16, v251, s[48:49]
	v_add_f32_e32 v251, v115, v238
	v_cndmask_b32_e64 v67, v16, v251, s[52:53]
	ds_read_b32 v25, v207 offset:316
	ds_read_b32 v243, v207 offset:188
	ds_read_b32 v26, v207 offset:320
	ds_read_b32 v244, v207 offset:192
	ds_read_b32 v27, v207 offset:324
	ds_read_b32 v245, v207 offset:196
	ds_read_b32 v28, v207 offset:328
	ds_read_b32 v246, v207 offset:200
	s_waitcnt lgkmcnt(8)
	v_add_f32_e32 v251, v116, v239
	v_cndmask_b32_e64 v68, v16, v251, s[56:57]
	v_add_f32_e32 v251, v117, v240
	v_cndmask_b32_e64 v69, v16, v251, s[60:61]
	v_add_f32_e32 v251, v118, v241
	v_cndmask_b32_e64 v70, v16, v251, s[64:65]
	v_add_f32_e32 v251, v119, v242
	v_cndmask_b32_e64 v71, v16, v251, s[68:69]
	ds_read_b32 v29, v207 offset:348
	ds_read_b32 v247, v207 offset:220
	ds_read_b32 v30, v207 offset:352
	ds_read_b32 v248, v207 offset:224
	ds_read_b32 v31, v207 offset:356
	ds_read_b32 v249, v207 offset:228
	ds_read_b32 v95, v207 offset:360
	ds_read_b32 v250, v207 offset:232
	s_waitcnt lgkmcnt(8)
	v_add_f32_e32 v251, v120, v243
	v_cndmask_b32_e64 v72, v16, v251, s[16:17]
	v_add_f32_e32 v251, v121, v244
	v_cndmask_b32_e64 v73, v16, v251, s[18:19]
	v_add_f32_e32 v251, v122, v245
	v_cndmask_b32_e64 v74, v16, v251, s[20:21]
	v_add_f32_e32 v251, v123, v246
	v_cndmask_b32_e64 v75, v16, v251, s[22:23]
	v_add_f32_e32 v17, v96, v17
	v_cndmask_b32_e64 v80, v16, v17, s[42:43]
	v_add_f32_e32 v17, v97, v18
	v_cndmask_b32_e64 v81, v16, v17, s[46:47]
	v_add_f32_e32 v17, v98, v19
	v_cndmask_b32_e64 v82, v16, v17, s[50:51]
	v_add_f32_e32 v17, v99, v20
	v_cndmask_b32_e64 v83, v16, v17, s[54:55]
	v_add_f32_e32 v17, v100, v21
	v_cndmask_b32_e64 v84, v16, v17, s[58:59]
	v_add_f32_e32 v17, v101, v22
	v_cndmask_b32_e64 v85, v16, v17, s[62:63]
	v_add_f32_e32 v17, v102, v23
	v_cndmask_b32_e64 v86, v16, v17, s[66:67]
	v_add_f32_e32 v17, v103, v24
	v_cndmask_b32_e64 v87, v16, v17, s[70:71]
	s_waitcnt lgkmcnt(7)
	v_add_f32_e32 v17, v104, v25
	v_cndmask_b32_e64 v88, v16, v17, s[72:73]
	s_waitcnt lgkmcnt(6)
	v_add_f32_e32 v17, v105, v26
	v_cndmask_b32_e64 v89, v16, v17, s[74:75]
	s_waitcnt lgkmcnt(5)
	v_add_f32_e32 v17, v106, v27
	v_cndmask_b32_e64 v90, v16, v17, s[76:77]
	s_waitcnt lgkmcnt(4)
	v_add_f32_e32 v17, v107, v28
	v_cndmask_b32_e64 v91, v16, v17, s[78:79]
	s_waitcnt lgkmcnt(3)
	v_add_f32_e32 v17, v108, v29
	v_cndmask_b32_e64 v92, v16, v17, s[80:81]
	s_waitcnt lgkmcnt(2)
	v_add_f32_e32 v17, v109, v30
	v_cndmask_b32_e64 v93, v16, v17, s[82:83]
	s_waitcnt lgkmcnt(1)
	v_add_f32_e32 v17, v110, v31
	v_cndmask_b32_e64 v94, v16, v17, s[84:85]
	s_waitcnt lgkmcnt(0)
	v_add_f32_e32 v17, v111, v95
	v_cndmask_b32_e64 v95, v16, v17, s[86:87]
	v_add_f32_e32 v251, v124, v247
	v_cndmask_b32_e64 v76, v16, v251, s[24:25]
	v_add_f32_e32 v251, v125, v248
	v_cndmask_b32_e64 v77, v16, v251, s[26:27]
	v_add_f32_e32 v251, v126, v249
	v_cndmask_b32_e64 v78, v16, v251, s[28:29]
	v_add_f32_e32 v251, v127, v250
	v_cndmask_b32_e64 v79, v16, v251, s[30:31]
	s_branch .LBB0_1789
